# v63 + rare overflow-path trampolines recompute the stage offsets (robustness fix, never taken on these inputs); code placement kept at the same 64-byte phase
# speedup vs baseline: 1.0212x; 1.0019x over previous
; __device__ __forceinline__ float swap32_max(float m) { auto rr = __builtin_amdgcn_permlane32_swap(__float_as_uint(m), __float_as_uint(m), false, false); return fmaxf(__uint_as_float(rr[0]), __uint_as_float(rr[1])); }
; __device__ __forceinline__ s16x4 vtr(ldsp p) { return __builtin_bit_cast(s16x4, __builtin_amdgcn_ds_read_tr16_b64_v4i16((LAS v4i16_t*)p)); }
; #define MASK_BLOCK() do { if (kt == 0 || kt >= diag0) { \
;             _Pragma("unroll") for (int r = 0; r < 16; ++r) { const int kpp = 64 * kt + crow(r, hi); \
;                 if (kpp < 48 || kpp > q_pp) s0[r] = -INFINITY; \
;                 if (kpp + 32 < 48 || kpp + 32 > q_pp) s1[r] = -INFINITY; } } } while (0)
; template <bool DIFF>
; __device__ __forceinline__ void attn_unit(const AttnP& A, int b, int h, int qi, ldsp lds) {
;     ...
;                 if (__any(psa + psb > 1.0e18f)) { full = true; QK_BLOCK();
; #pragma unroll
;                     for (int t = 0; t < 2; ++t)
; #pragma unroll
;                         for (int j = 0; j < 4; ++j) { vlo[t * 4 + j] = vtr(Vb + trb + (16 * j) * VP + t * 64); vhi[t * 4 + j] = vtr(Vb + trb + (16 * j + 8) * VP + t * 64); }
;                     MASK_BLOCK(); }
;             }
;             if (full) {
;                 float ma = fmaxf(fmaxf(s0[0], s0[1]), s1[0]), mb = fmaxf(fmaxf(s0[2], s0[3]), s1[1]);
;                 ma = fmaxf(fmaxf(ma, s1[2]), s1[3]);
; #pragma unroll
;                 for (int r = 4; r < 16; r += 4) { ma = fmaxf(fmaxf(ma, s0[r]), s0[r + 1]); mb = fmaxf(fmaxf(mb, s0[r + 2]), s0[r + 3]); ma = fmaxf(fmaxf(ma, s1[r]), s1[r + 1]); mb = fmaxf(fmaxf(mb, s1[r + 2]), s1[r + 3]); }
;                 const float rm = swap32_max(fmaxf(ma, mb));
;                 const float dl = (kt == kt0) ? ((rm == -INFINITY) ? 0.f : rm) : fmaxf(rm, 0.f);
;                 mhat += dl;
; #pragma unroll
;                 for (int r = 0; r < 16; ++r) { s0[r] -= dl; s1[r] -= dl; negm[r] = -mhat; }
;                 const float f = (kt == kt0) ? 1.0f : __builtin_amdgcn_exp2f(-dl);
;                 l_run *= f;
; #pragma unroll
;                 for (int t = 0; t < NTD; ++t)
; #pragma unroll
;                     for (int r = 0; r < 16; ++r) o[t][r] *= f;
;                 EXPSUM_BLOCK();
;             }
.Lfa_s_slow:
	s_bitcmp1_b32 s99, 0
	s_cselect_b32 s74, 0x5500, 0
	s_sub_i32 s75, 0x5500, s74
	s_mov_b64 s[48:49], 0
	s_branch .Lfx6_full

; __device__ __forceinline__ float swap32_max(float m) { auto rr = __builtin_amdgcn_permlane32_swap(__float_as_uint(m), __float_as_uint(m), false, false); return fmaxf(__uint_as_float(rr[0]), __uint_as_float(rr[1])); }
; __device__ __forceinline__ s16x4 vtr(ldsp p) { return __builtin_bit_cast(s16x4, __builtin_amdgcn_ds_read_tr16_b64_v4i16((LAS v4i16_t*)p)); }
; #define MASK_BLOCK() do { if (kt == 0 || kt >= diag0) { \
;             _Pragma("unroll") for (int r = 0; r < 16; ++r) { const int kpp = 64 * kt + crow(r, hi); \
;                 if (kpp < 48 || kpp > q_pp) s0[r] = -INFINITY; \
;                 if (kpp + 32 < 48 || kpp + 32 > q_pp) s1[r] = -INFINITY; } } } while (0)
; template <bool DIFF>
; __device__ __forceinline__ void attn_unit(const AttnP& A, int b, int h, int qi, ldsp lds) {
;     ...
;                 if (__any(psa + psb > 1.0e18f)) { full = true; QK_BLOCK();
; #pragma unroll
;                     for (int t = 0; t < 2; ++t)
; #pragma unroll
;                         for (int j = 0; j < 4; ++j) { vlo[t * 4 + j] = vtr(Vb + trb + (16 * j) * VP + t * 64); vhi[t * 4 + j] = vtr(Vb + trb + (16 * j + 8) * VP + t * 64); }
;                     MASK_BLOCK(); }
;             }
;             if (full) {
;                 float ma = fmaxf(fmaxf(s0[0], s0[1]), s1[0]), mb = fmaxf(fmaxf(s0[2], s0[3]), s1[1]);
;                 ma = fmaxf(fmaxf(ma, s1[2]), s1[3]);
; #pragma unroll
;                 for (int r = 4; r < 16; r += 4) { ma = fmaxf(fmaxf(ma, s0[r]), s0[r + 1]); mb = fmaxf(fmaxf(mb, s0[r + 2]), s0[r + 3]); ma = fmaxf(fmaxf(ma, s1[r]), s1[r + 1]); mb = fmaxf(fmaxf(mb, s1[r + 2]), s1[r + 3]); }
;                 const float rm = swap32_max(fmaxf(ma, mb));
;                 const float dl = (kt == kt0) ? ((rm == -INFINITY) ? 0.f : rm) : fmaxf(rm, 0.f);
;                 mhat += dl;
; #pragma unroll
;                 for (int r = 0; r < 16; ++r) { s0[r] -= dl; s1[r] -= dl; negm[r] = -mhat; }
;                 const float f = (kt == kt0) ? 1.0f : __builtin_amdgcn_exp2f(-dl);
;                 l_run *= f;
; #pragma unroll
;                 for (int t = 0; t < NTD; ++t)
; #pragma unroll
;                     for (int r = 0; r < 16; ++r) o[t][r] *= f;
;                 EXPSUM_BLOCK();
;             }
.Lfb_s_slow:
	s_nop 0
	s_bitcmp1_b32 s99, 0
	s_cselect_b32 s74, 0x5500, 0
	s_sub_i32 s75, 0x5500, s74
	s_mov_b64 s[48:49], 0
	s_branch .Lfx13_full

; __device__ __forceinline__ float swap32_max(float m) { auto rr = __builtin_amdgcn_permlane32_swap(__float_as_uint(m), __float_as_uint(m), false, false); return fmaxf(__uint_as_float(rr[0]), __uint_as_float(rr[1])); }
; __device__ __forceinline__ s16x4 vtr(ldsp p) { return __builtin_bit_cast(s16x4, __builtin_amdgcn_ds_read_tr16_b64_v4i16((LAS v4i16_t*)p)); }
; #define MASK_BLOCK() do { if (kt == 0 || kt >= diag0) { \
;             _Pragma("unroll") for (int r = 0; r < 16; ++r) { const int kpp = 64 * kt + crow(r, hi); \
;                 if (kpp < 48 || kpp > q_pp) s0[r] = -INFINITY; \
;                 if (kpp + 32 < 48 || kpp + 32 > q_pp) s1[r] = -INFINITY; } } } while (0)
; template <bool DIFF>
; __device__ __forceinline__ void attn_unit(const AttnP& A, int b, int h, int qi, ldsp lds) {
;     ...
;                 if (__any(psa + psb > 1.0e18f)) { full = true; QK_BLOCK();
; #pragma unroll
;                     for (int t = 0; t < 2; ++t)
; #pragma unroll
;                         for (int j = 0; j < 4; ++j) { vlo[t * 4 + j] = vtr(Vb + trb + (16 * j) * VP + t * 64); vhi[t * 4 + j] = vtr(Vb + trb + (16 * j + 8) * VP + t * 64); }
;                     MASK_BLOCK(); }
;             }
;             if (full) {
;                 float ma = fmaxf(fmaxf(s0[0], s0[1]), s1[0]), mb = fmaxf(fmaxf(s0[2], s0[3]), s1[1]);
;                 ma = fmaxf(fmaxf(ma, s1[2]), s1[3]);
; #pragma unroll
;                 for (int r = 4; r < 16; r += 4) { ma = fmaxf(fmaxf(ma, s0[r]), s0[r + 1]); mb = fmaxf(fmaxf(mb, s0[r + 2]), s0[r + 3]); ma = fmaxf(fmaxf(ma, s1[r]), s1[r + 1]); mb = fmaxf(fmaxf(mb, s1[r + 2]), s1[r + 3]); }
;                 const float rm = swap32_max(fmaxf(ma, mb));
;                 const float dl = (kt == kt0) ? ((rm == -INFINITY) ? 0.f : rm) : fmaxf(rm, 0.f);
;                 mhat += dl;
; #pragma unroll
;                 for (int r = 0; r < 16; ++r) { s0[r] -= dl; s1[r] -= dl; negm[r] = -mhat; }
;                 const float f = (kt == kt0) ? 1.0f : __builtin_amdgcn_exp2f(-dl);
;                 l_run *= f;
; #pragma unroll
;                 for (int t = 0; t < NTD; ++t)
; #pragma unroll
;                     for (int r = 0; r < 16; ++r) o[t][r] *= f;
;                 EXPSUM_BLOCK();
;             }
.Lda_s_slow:
	s_bitcmp1_b32 s75, 0
	s_cselect_b32 s45, 0x9500, 0
	s_sub_i32 s71, 0x9500, s45
	s_mov_b64 s[48:49], -1
	s_branch .Lda5_full
